# out-proj residual epilogue: uniform one-block-ahead prefetch with two alternating 8-reg sets v168-175/v176-183 (loads for block k+1 issued before block k's waits, vmcnt 4/3), on top of graduated waits
# speedup vs baseline: 1.0058x; 1.0058x over previous
; __device__ __forceinline__ unsigned cvt_pk_bf16(float lo, float hi) { unsigned r; asm volatile("v_cvt_pk_bf16_f32 %0, %1, %2" : "=v"(r) : "v"(lo), "v"(hi)); return r; }
;     __device__ __forceinline__ void operator()(const f32x4 (&acc)[2][2][4][2], const Unit& u, int wr, int wc, int fr, int fq) const {
;     ...
;         if (F32BASE) {
; #pragma unroll
;             for (int ai = 0; ai < 2; ++ai)
; #pragma unroll
;                 for (int m = 0; m < 4; ++m) { const size_t roff = (size_t)(row0 + ai * HALF + m * 16) * ldc + col0;
; #pragma unroll
;                     for (int bj = 0; bj < 2; ++bj) { const size_t off = roff + bj * HALF; const f32x4 v0 = acc[ai][bj][m][0] + *(const f32x4*)(basef + off), v1 = acc[ai][bj][m][1] + *(const f32x4*)(basef + off + 4);
;                         u32x4 w; w.x = cvt_pk_bf16(v0[0], v0[1]); w.y = cvt_pk_bf16(v0[2], v0[3]); w.z = cvt_pk_bf16(v1[0], v1[1]); w.w = cvt_pk_bf16(v1[2], v1[3]);
;                         *(u32x4*)(outb + off) = w; }
;                     if (m & 1) asm volatile("" ::: "memory"); }
.LBB0_248:
	v_lshl_add_u32 v148, s68, 8, v150
	v_lshl_or_b32 v146, s24, 8, v152
	v_ashrrev_i32_e32 v149, 31, v148
	v_ashrrev_i32_e32 v147, 31, v146
	v_lshlrev_b64 v[144:145], 11, v[148:149]
	v_lshl_add_u64 v[144:145], v[144:145], 0, v[146:147]
	v_lshl_add_u64 v[164:165], v[144:145], 2, s[36:37]
	global_load_dwordx4 v[156:159], v[164:165], off
	global_load_dwordx4 v[160:163], v[164:165], off offset:16
	global_load_dwordx4 v[176:179], v[164:165], off offset:512
	global_load_dwordx4 v[180:183], v[164:165], off offset:528
	v_lshl_add_u64 v[166:167], v[144:145], 1, s[52:53]
	s_mov_b64 s[24:25], 0x40000
	s_andn2_b64 vcc, exec, s[4:5]
	s_mov_b64 s[4:5], -1
	s_waitcnt vmcnt(2)
	v_pk_add_f32 v[124:125], v[124:125], v[156:157]
	v_pk_add_f32 v[156:157], v[122:123], v[162:163]
	v_pk_add_f32 v[122:123], v[120:121], v[160:161]
	v_pk_add_f32 v[126:127], v[126:127], v[158:159]
	v_cvt_pk_bf16_f32 v120, v124, v125
	s_nop 0
	v_cvt_pk_bf16_f32 v121, v126, v127
	v_cvt_pk_bf16_f32 v122, v122, v123
	v_cvt_pk_bf16_f32 v123, v156, v157
	global_store_dwordx4 v[166:167], v[120:123], off
	s_nop 1
	s_nop 0
	v_or_b32_e32 v156, 16, v148
	v_ashrrev_i32_e32 v157, 31, v156
	v_lshlrev_b64 v[156:157], 11, v[156:157]
	v_lshl_add_u64 v[156:157], v[156:157], 0, v[146:147]
	v_lshl_add_u64 v[158:159], v[156:157], 2, s[36:37]
	global_load_dwordx4 v[168:171], v[158:159], off
	global_load_dwordx4 v[172:175], v[158:159], off offset:16
	s_waitcnt vmcnt(4)
	v_pk_add_f32 v[116:117], v[116:117], v[176:177]
	s_waitcnt vmcnt(3)
	v_pk_add_f32 v[120:121], v[114:115], v[182:183]
	v_pk_add_f32 v[114:115], v[112:113], v[180:181]
	v_pk_add_f32 v[118:119], v[118:119], v[178:179]
	v_cvt_pk_bf16_f32 v112, v116, v117
	s_nop 0
	v_cvt_pk_bf16_f32 v113, v118, v119
	v_cvt_pk_bf16_f32 v114, v114, v115
	v_cvt_pk_bf16_f32 v115, v120, v121
	global_store_dwordx4 v[166:167], v[112:115], off offset:256
	s_nop 1
	s_nop 0
	v_lshl_add_u64 v[120:121], v[156:157], 1, s[52:53]
	global_load_dwordx4 v[176:179], v[158:159], off offset:512
	global_load_dwordx4 v[180:183], v[158:159], off offset:528
	s_waitcnt vmcnt(4)
	v_pk_add_f32 v[108:109], v[108:109], v[168:169]
	s_waitcnt vmcnt(3)
	v_pk_add_f32 v[112:113], v[106:107], v[174:175]
	v_pk_add_f32 v[106:107], v[104:105], v[172:173]
	v_pk_add_f32 v[110:111], v[110:111], v[170:171]
	v_cvt_pk_bf16_f32 v104, v108, v109
	s_nop 0
	v_cvt_pk_bf16_f32 v105, v110, v111
	v_cvt_pk_bf16_f32 v106, v106, v107
	v_cvt_pk_bf16_f32 v107, v112, v113
	global_store_dwordx4 v[120:121], v[104:107], off
	s_nop 1
	s_nop 0
	v_or_b32_e32 v112, 32, v148
	v_ashrrev_i32_e32 v113, 31, v112
	v_lshlrev_b64 v[112:113], 11, v[112:113]
	v_lshl_add_u64 v[112:113], v[112:113], 0, v[146:147]
	v_lshl_add_u64 v[114:115], v[112:113], 2, s[36:37]
	global_load_dwordx4 v[168:171], v[114:115], off
	global_load_dwordx4 v[172:175], v[114:115], off offset:16
	s_waitcnt vmcnt(4)
	v_pk_add_f32 v[100:101], v[100:101], v[176:177]
	s_waitcnt vmcnt(3)
	v_pk_add_f32 v[104:105], v[98:99], v[182:183]
	v_pk_add_f32 v[98:99], v[96:97], v[180:181]
	v_pk_add_f32 v[102:103], v[102:103], v[178:179]
	v_cvt_pk_bf16_f32 v96, v100, v101
	s_nop 0
	v_cvt_pk_bf16_f32 v97, v102, v103
	v_cvt_pk_bf16_f32 v98, v98, v99
	v_cvt_pk_bf16_f32 v99, v104, v105
	global_store_dwordx4 v[120:121], v[96:99], off offset:256
	s_nop 1
	v_lshl_add_u64 v[104:105], v[112:113], 1, s[52:53]
	global_load_dwordx4 v[176:179], v[114:115], off offset:512
	global_load_dwordx4 v[180:183], v[114:115], off offset:528
	s_waitcnt vmcnt(4)
	v_pk_add_f32 v[92:93], v[92:93], v[168:169]
	s_waitcnt vmcnt(3)
	v_pk_add_f32 v[96:97], v[90:91], v[174:175]
	v_pk_add_f32 v[90:91], v[88:89], v[172:173]
	v_pk_add_f32 v[94:95], v[94:95], v[170:171]
	v_cvt_pk_bf16_f32 v88, v92, v93
	s_nop 0
	v_cvt_pk_bf16_f32 v89, v94, v95
	v_cvt_pk_bf16_f32 v90, v90, v91
	v_cvt_pk_bf16_f32 v91, v96, v97
	global_store_dwordx4 v[104:105], v[88:91], off
	s_nop 1
	s_nop 0
	v_or_b32_e32 v96, 48, v148
	v_ashrrev_i32_e32 v97, 31, v96
	v_lshlrev_b64 v[96:97], 11, v[96:97]
	v_lshl_add_u64 v[96:97], v[96:97], 0, v[146:147]
	v_lshl_add_u64 v[98:99], v[96:97], 2, s[36:37]
	global_load_dwordx4 v[168:171], v[98:99], off
	global_load_dwordx4 v[172:175], v[98:99], off offset:16
	s_waitcnt vmcnt(4)
	v_pk_add_f32 v[84:85], v[84:85], v[176:177]
	s_waitcnt vmcnt(3)
	v_pk_add_f32 v[88:89], v[82:83], v[182:183]
	v_pk_add_f32 v[82:83], v[80:81], v[180:181]
	v_pk_add_f32 v[86:87], v[86:87], v[178:179]
	v_cvt_pk_bf16_f32 v80, v84, v85
	s_nop 0
	v_cvt_pk_bf16_f32 v81, v86, v87
	v_cvt_pk_bf16_f32 v82, v82, v83
	v_cvt_pk_bf16_f32 v83, v88, v89
	global_store_dwordx4 v[104:105], v[80:83], off offset:256
	s_nop 1
	s_nop 0
	v_lshl_add_u64 v[88:89], v[96:97], 1, s[52:53]
	global_load_dwordx4 v[176:179], v[98:99], off offset:512
	global_load_dwordx4 v[180:183], v[98:99], off offset:528
	s_waitcnt vmcnt(4)
	v_pk_add_f32 v[76:77], v[76:77], v[168:169]
	s_waitcnt vmcnt(3)
	v_pk_add_f32 v[80:81], v[74:75], v[174:175]
	v_pk_add_f32 v[74:75], v[72:73], v[172:173]
	v_pk_add_f32 v[78:79], v[78:79], v[170:171]
	v_cvt_pk_bf16_f32 v72, v76, v77
	s_nop 0
	v_cvt_pk_bf16_f32 v73, v78, v79
	v_cvt_pk_bf16_f32 v74, v74, v75
	v_cvt_pk_bf16_f32 v75, v80, v81
	global_store_dwordx4 v[88:89], v[72:75], off
	s_nop 1
	s_nop 0
	v_lshl_add_u64 v[80:81], v[144:145], 0, s[24:25]
	v_lshl_add_u64 v[82:83], v[80:81], 2, s[36:37]
	s_mov_b64 s[24:25], 0x48000
	global_load_dwordx4 v[168:171], v[82:83], off
	global_load_dwordx4 v[172:175], v[82:83], off offset:16
	s_waitcnt vmcnt(4)
; __device__ __forceinline__ unsigned cvt_pk_bf16(float lo, float hi) { unsigned r; asm volatile("v_cvt_pk_bf16_f32 %0, %1, %2" : "=v"(r) : "v"(lo), "v"(hi)); return r; }
;     __device__ __forceinline__ void operator()(const f32x4 (&acc)[2][2][4][2], const Unit& u, int wr, int wc, int fr, int fq) const {
;     ...
;         if (F32BASE) {
; #pragma unroll
;             for (int ai = 0; ai < 2; ++ai)
; #pragma unroll
;                 for (int m = 0; m < 4; ++m) { const size_t roff = (size_t)(row0 + ai * HALF + m * 16) * ldc + col0;
; #pragma unroll
;                     for (int bj = 0; bj < 2; ++bj) { const size_t off = roff + bj * HALF; const f32x4 v0 = acc[ai][bj][m][0] + *(const f32x4*)(basef + off), v1 = acc[ai][bj][m][1] + *(const f32x4*)(basef + off + 4);
;                         u32x4 w; w.x = cvt_pk_bf16(v0[0], v0[1]); w.y = cvt_pk_bf16(v0[2], v0[3]); w.z = cvt_pk_bf16(v1[0], v1[1]); w.w = cvt_pk_bf16(v1[2], v1[3]);
;                         *(u32x4*)(outb + off) = w; }
;                     if (m & 1) asm volatile("" ::: "memory"); }
	v_pk_add_f32 v[68:69], v[68:69], v[176:177]
	s_waitcnt vmcnt(3)
	v_pk_add_f32 v[72:73], v[66:67], v[182:183]
	v_pk_add_f32 v[66:67], v[64:65], v[180:181]
	v_pk_add_f32 v[70:71], v[70:71], v[178:179]
	v_cvt_pk_bf16_f32 v64, v68, v69
	s_nop 0
	v_cvt_pk_bf16_f32 v65, v70, v71
	v_cvt_pk_bf16_f32 v66, v66, v67
	v_cvt_pk_bf16_f32 v67, v72, v73
	global_store_dwordx4 v[88:89], v[64:67], off offset:256
	s_nop 1
	v_lshl_add_u64 v[72:73], v[80:81], 1, s[52:53]
	global_load_dwordx4 v[176:179], v[82:83], off offset:512
	global_load_dwordx4 v[180:183], v[82:83], off offset:528
	s_waitcnt vmcnt(4)
	v_pk_add_f32 v[60:61], v[60:61], v[168:169]
	s_waitcnt vmcnt(3)
	v_pk_add_f32 v[64:65], v[58:59], v[174:175]
	v_pk_add_f32 v[58:59], v[56:57], v[172:173]
	v_pk_add_f32 v[62:63], v[62:63], v[170:171]
	v_cvt_pk_bf16_f32 v56, v60, v61
	s_nop 0
	v_cvt_pk_bf16_f32 v57, v62, v63
	v_cvt_pk_bf16_f32 v58, v58, v59
	v_cvt_pk_bf16_f32 v59, v64, v65
	global_store_dwordx4 v[72:73], v[56:59], off
	s_nop 1
	s_nop 0
	v_lshl_add_u64 v[64:65], v[144:145], 0, s[24:25]
	v_lshl_add_u64 v[66:67], v[64:65], 2, s[36:37]
	global_load_dwordx4 v[168:171], v[66:67], off
	global_load_dwordx4 v[172:175], v[66:67], off offset:16
	s_waitcnt vmcnt(4)
	v_pk_add_f32 v[52:53], v[52:53], v[176:177]
	s_waitcnt vmcnt(3)
	v_pk_add_f32 v[56:57], v[50:51], v[182:183]
	v_pk_add_f32 v[50:51], v[48:49], v[180:181]
	v_pk_add_f32 v[54:55], v[54:55], v[178:179]
	v_cvt_pk_bf16_f32 v48, v52, v53
	s_nop 0
	v_cvt_pk_bf16_f32 v49, v54, v55
	v_cvt_pk_bf16_f32 v50, v50, v51
	v_cvt_pk_bf16_f32 v51, v56, v57
	global_store_dwordx4 v[72:73], v[48:51], off offset:256
	s_nop 1
	s_nop 0
	v_lshl_add_u64 v[56:57], v[64:65], 1, s[52:53]
	global_load_dwordx4 v[176:179], v[66:67], off offset:512
	global_load_dwordx4 v[180:183], v[66:67], off offset:528
	s_waitcnt vmcnt(4)
	v_pk_add_f32 v[44:45], v[44:45], v[168:169]
	s_waitcnt vmcnt(3)
	v_pk_add_f32 v[48:49], v[42:43], v[174:175]
	v_pk_add_f32 v[42:43], v[40:41], v[172:173]
	v_pk_add_f32 v[46:47], v[46:47], v[170:171]
	v_cvt_pk_bf16_f32 v40, v44, v45
	s_nop 0
	v_cvt_pk_bf16_f32 v41, v46, v47
	v_cvt_pk_bf16_f32 v42, v42, v43
	v_cvt_pk_bf16_f32 v43, v48, v49
	global_store_dwordx4 v[56:57], v[40:43], off
	s_nop 1
	s_nop 0
	v_lshl_add_u64 v[48:49], v[144:145], 0, s[44:45]
	v_lshl_add_u64 v[50:51], v[48:49], 2, s[36:37]
	global_load_dwordx4 v[168:171], v[50:51], off
	global_load_dwordx4 v[172:175], v[50:51], off offset:16
	s_waitcnt vmcnt(4)
	v_pk_add_f32 v[36:37], v[36:37], v[176:177]
	s_waitcnt vmcnt(3)
	v_pk_add_f32 v[40:41], v[34:35], v[182:183]
	v_pk_add_f32 v[34:35], v[32:33], v[180:181]
	v_pk_add_f32 v[38:39], v[38:39], v[178:179]
	v_cvt_pk_bf16_f32 v32, v36, v37
	s_nop 0
	v_cvt_pk_bf16_f32 v33, v38, v39
	v_cvt_pk_bf16_f32 v34, v34, v35
	v_cvt_pk_bf16_f32 v35, v40, v41
	global_store_dwordx4 v[56:57], v[32:35], off offset:256
	s_nop 1
	v_lshl_add_u64 v[40:41], v[48:49], 1, s[52:53]
	global_load_dwordx4 v[176:179], v[50:51], off offset:512
	global_load_dwordx4 v[180:183], v[50:51], off offset:528
	s_waitcnt vmcnt(4)
	v_pk_add_f32 v[28:29], v[28:29], v[168:169]
	s_waitcnt vmcnt(3)
	v_pk_add_f32 v[32:33], v[26:27], v[174:175]
	v_pk_add_f32 v[26:27], v[24:25], v[172:173]
	v_pk_add_f32 v[30:31], v[30:31], v[170:171]
	v_cvt_pk_bf16_f32 v24, v28, v29
	s_nop 0
	v_cvt_pk_bf16_f32 v25, v30, v31
	v_cvt_pk_bf16_f32 v26, v26, v27
	v_cvt_pk_bf16_f32 v27, v32, v33
	global_store_dwordx4 v[40:41], v[24:27], off
	s_nop 1
	s_nop 0
	v_lshl_add_u64 v[32:33], v[144:145], 0, s[48:49]
	v_lshl_add_u64 v[34:35], v[32:33], 2, s[36:37]
	global_load_dwordx4 v[168:171], v[34:35], off
	global_load_dwordx4 v[172:175], v[34:35], off offset:16
	s_waitcnt vmcnt(4)
	v_pk_add_f32 v[20:21], v[20:21], v[176:177]
	s_waitcnt vmcnt(3)
	v_pk_add_f32 v[24:25], v[18:19], v[182:183]
	v_pk_add_f32 v[18:19], v[16:17], v[180:181]
	v_pk_add_f32 v[22:23], v[22:23], v[178:179]
	v_cvt_pk_bf16_f32 v16, v20, v21
	s_nop 0
	v_cvt_pk_bf16_f32 v17, v22, v23
	v_cvt_pk_bf16_f32 v18, v18, v19
	v_cvt_pk_bf16_f32 v19, v24, v25
	global_store_dwordx4 v[40:41], v[16:19], off offset:256
	s_nop 1
	s_nop 0
	v_lshl_add_u64 v[24:25], v[32:33], 1, s[52:53]
	global_load_dwordx4 v[176:179], v[34:35], off offset:512
	global_load_dwordx4 v[180:183], v[34:35], off offset:528
	s_waitcnt vmcnt(4)
	v_pk_add_f32 v[12:13], v[12:13], v[168:169]
	s_waitcnt vmcnt(3)
	v_pk_add_f32 v[16:17], v[10:11], v[174:175]
	v_pk_add_f32 v[10:11], v[8:9], v[172:173]
	v_pk_add_f32 v[14:15], v[14:15], v[170:171]
	v_cvt_pk_bf16_f32 v8, v12, v13
	s_nop 0
	v_cvt_pk_bf16_f32 v9, v14, v15
	v_cvt_pk_bf16_f32 v10, v10, v11
	v_cvt_pk_bf16_f32 v11, v16, v17
	global_store_dwordx4 v[24:25], v[8:11], off
	s_nop 1
	s_nop 0
	s_waitcnt vmcnt(2)
	v_pk_add_f32 v[4:5], v[4:5], v[176:177]
	s_waitcnt vmcnt(1)
	v_pk_add_f32 v[8:9], v[2:3], v[182:183]
	v_pk_add_f32 v[2:3], v[0:1], v[180:181]
	v_pk_add_f32 v[6:7], v[6:7], v[178:179]
	v_cvt_pk_bf16_f32 v0, v4, v5
	s_nop 0
	v_cvt_pk_bf16_f32 v1, v6, v7
	v_cvt_pk_bf16_f32 v2, v2, v3
	v_cvt_pk_bf16_f32 v3, v8, v9
	global_store_dwordx4 v[24:25], v[0:3], off offset:256
	s_cbranch_vccnz .LBB0_237
	s_andn2_b64 vcc, exec, s[6:7]
	s_cbranch_vccnz .LBB0_236
	s_barrier
	s_branch .LBB0_236
